# SGU block preheader: issue the four w_s tile loads together (one wait) + drop loop-top waits that only covered stores
# speedup vs baseline: 1.0079x; 1.0079x over previous
; #define SGU_LOAD(ch) do { _Pragma("unroll") for (int i = 0; i < 4; ++i) pv[i] = *(const u32x4*)(Z + (size_t)((ch) * 128 + lrow + 32 * i) * ZW + ZSV + g * 128 + cs); } while (0)
; PHASE_FN void sgu_block(const Params& p, unsigned char* lds, int l, int g, int ch0, int nch) {
;     ...
;     const int wid = __builtin_amdgcn_readfirstlane(tid >> 6), lane = tid & 63, lr = lane & 15, q4 = lane >> 4;
;     const bf16_t* __restrict__ Z = (const bf16_t*)(ws + WS_Z); bf16_t* __restrict__ MIX = (bf16_t*)(ws + WS_MIX);
;     const bf16_t* __restrict__ wsb = (const bf16_t*)(ws + WS_WSB) + (size_t)(l * 4 + g) * 128 * 128;
;     bf16_t* wl = (bf16_t*)(lds + L_SW);
;     const int lrow = tid >> 4, cs = (tid & 15) * 8;
; #pragma unroll
;     for (int i = 0; i < 4; ++i) *(u32x4*)(wl + (lrow + 32 * i) * SP + cs) = *(const u32x4*)(wsb + (size_t)(lrow + 32 * i) * 128 + cs);
;     const float* ngp = p.sgu_norm_g + (size_t)l * 512 + g * 128 + cs; const f32x4 g0 = *(const f32x4*)ngp, g1 = *(const f32x4*)(ngp + 4);
;     float bs[8];
; #pragma unroll
;     for (int pb = 0; pb < 8; ++pb) bs[pb] = p.b_s[(size_t)l * 512 + g * 128 + 16 * pb + lr];
;     const int ocol = g * 128 + 16 * wid + 4 * q4;
;     u32x4 pv[4];
;     ...
;     SGU_LOAD(ch0);
.LBB0_252:
	v_mov_b32_e32 v6, v206
	s_lshl_b32 s10, s9, 15
	s_add_i32 s10, s10, s4
	v_lshlrev_b32_e32 v0, 3, v6
	s_add_u32 s10, s91, s10
	v_readlane_b32 s11, v248, 34
	v_ashrrev_i32_e32 v24, 4, v6
	v_and_b32_e32 v40, 0x78, v0
	s_addc_u32 s11, s11, 0
	v_lshlrev_b32_e32 v152, 1, v40
	v_ashrrev_i32_e32 v25, 31, v24
	v_lshl_add_u64 v[0:1], s[10:11], 0, v[152:153]
	v_lshlrev_b64 v[2:3], 8, v[24:25]
	v_lshl_add_u64 v[4:5], v[0:1], 0, v[2:3]
	global_load_dwordx4 v[0:3], v[4:5], off
	s_movk_i32 s10, 0x110
	v_mul_lo_u32 v41, v24, s10
	v_add3_u32 v7, 0, v152, v41
	s_movk_i32 s10, 0x4000
	s_lshl_b32 s76, s9, 7
	v_and_b32_e32 v76, 15, v6
	v_lshlrev_b32_e32 v8, 2, v76
	v_readfirstlane_b32 s14, v6
	v_bfe_u32 v28, v6, 4, 2
	v_mov_b64_e32 v[20:21], s[60:61]
	v_and_b32_e32 v27, 64, v209
	v_xor_b32_e32 v25, 1, v209
	v_add_u32_e32 v27, 64, v27
	v_mul_u32_u24_e32 v89, 0x880, v28
	v_add_u32_e32 v90, s25, v24
	v_add_u32_e32 v91, s25, v76
	v_add_co_u32_e32 v12, vcc, s35, v4
	s_nop 1
	v_addc_co_u32_e32 v13, vcc, 0, v5, vcc
	global_load_dwordx4 v[12:15], v[12:13], off
	v_add_co_u32_e32 v16, vcc, s10, v4
	s_movk_i32 s10, 0x6000
	s_nop 0
	v_addc_co_u32_e32 v17, vcc, 0, v5, vcc
	global_load_dwordx4 v[16:19], v[16:17], off
	v_add_co_u32_e32 v252, vcc, s10, v4
	s_lshl_b64 s[10:11], s[76:77], 2
	s_nop 0
	v_addc_co_u32_e32 v253, vcc, 0, v5, vcc
	global_load_dwordx4 v[252:255], v[252:253], off
	s_add_u32 s12, s5, s10
	s_addc_u32 s13, s6, s11
	s_add_u32 s10, s7, s10
	v_lshlrev_b32_e32 v4, 2, v40
	s_addc_u32 s11, s8, s11
	s_waitcnt vmcnt(0)
	ds_write_b128 v7, v[0:3]
	ds_write_b128 v7, v[12:15] offset:8704
	ds_write_b128 v7, v[16:19] offset:17408
	ds_write_b128 v7, v[252:255] offset:26112
	global_load_dwordx4 v[0:3], v4, s[12:13]
	s_nop 0
	global_load_dwordx4 v[4:7], v4, s[12:13] offset:16
	s_nop 0
	global_load_dword v77, v8, s[10:11]
	global_load_dword v78, v8, s[10:11] offset:64
	global_load_dword v79, v8, s[10:11] offset:128
	global_load_dword v80, v8, s[10:11] offset:192
	global_load_dword v81, v8, s[10:11] offset:256
	global_load_dword v82, v8, s[10:11] offset:320
	global_load_dword v83, v8, s[10:11] offset:384
	global_load_dword v84, v8, s[10:11] offset:448
	v_readlane_b32 s11, v247, 35
	s_ashr_i32 s10, s14, 2
	s_and_b32 s10, s10, -16
	v_add_u32_e32 v22, s11, v24
	v_mad_i64_i32 v[8:9], s[12:13], v22, s1, v[20:21]
	s_lshl_b32 s12, s9, 8
	s_mov_b32 s13, s77
	v_lshl_add_u64 v[8:9], v[8:9], 0, s[12:13]
	v_add_u32_e32 v12, 32, v22
	v_lshl_add_u64 v[8:9], v[8:9], 0, v[152:153]
	s_movk_i32 s11, 0x1000
	v_mad_i64_i32 v[12:13], s[14:15], v12, s1, v[20:21]
	v_add_co_u32_e32 v8, vcc, s11, v8
	v_lshl_add_u64 v[12:13], v[12:13], 0, s[12:13]
	v_add_u32_e32 v16, 64, v22
	v_addc_co_u32_e32 v9, vcc, 0, v9, vcc
	v_lshl_add_u64 v[12:13], v[12:13], 0, v[152:153]
	v_mad_i64_i32 v[16:17], s[14:15], v16, s1, v[20:21]
	v_add_co_u32_e32 v12, vcc, s11, v12
	v_lshl_add_u64 v[16:17], v[16:17], 0, s[12:13]
	v_add_u32_e32 v22, 0x60, v22
	v_addc_co_u32_e32 v13, vcc, 0, v13, vcc
	v_lshl_add_u64 v[16:17], v[16:17], 0, v[152:153]
	v_mad_i64_i32 v[20:21], s[14:15], v22, s1, v[20:21]
	v_add_co_u32_e32 v16, vcc, s11, v16
	v_lshl_add_u64 v[20:21], v[20:21], 0, s[12:13]
	s_nop 0
	v_addc_co_u32_e32 v17, vcc, 0, v17, vcc
	v_lshl_add_u64 v[20:21], v[20:21], 0, v[152:153]
	v_add_co_u32_e32 v20, vcc, s11, v20
	global_load_dwordx4 v[8:11], v[8:9], off offset:512
	s_nop 0
	v_addc_co_u32_e32 v21, vcc, 0, v21, vcc
	global_load_dwordx4 v[12:15], v[12:13], off offset:512
	v_cmp_lt_i32_e32 vcc, v25, v27
	global_load_dwordx4 v[16:19], v[16:17], off offset:512
	s_add_i32 s11, s10, s76
	global_load_dwordx4 v[20:23], v[20:21], off offset:512
	v_cndmask_b32_e32 v25, v209, v25, vcc
	v_lshlrev_b32_e32 v85, 2, v25
	v_xor_b32_e32 v25, 2, v209
	v_cmp_lt_i32_e32 vcc, v25, v27
	v_lshl_or_b32 v26, v28, 2, s11
	s_lshl_b32 s76, s76, 1
	v_cndmask_b32_e32 v25, v209, v25, vcc
	v_lshlrev_b32_e32 v86, 2, v25
	v_xor_b32_e32 v25, 4, v209
	v_cmp_lt_i32_e32 vcc, v25, v27
	v_readlane_b32 s11, v246, 37
	s_mov_b32 s12, 0
	v_cndmask_b32_e32 v25, v209, v25, vcc
	v_lshlrev_b32_e32 v87, 2, v25
	v_xor_b32_e32 v25, 8, v209
	v_cmp_lt_i32_e32 vcc, v25, v27
	v_ashrrev_i32_e32 v27, 31, v26
	v_lshl_add_u64 v[42:43], v[26:27], 1, s[60:61]
	v_cndmask_b32_e32 v25, v209, v25, vcc
	v_lshlrev_b32_e32 v88, 2, v25
	v_lshl_add_u32 v25, v28, 4, 0
	v_mul_u32_u24_e32 v28, 0x110, v76
	v_add_u32_e32 v92, v25, v28
	v_lshlrev_b64 v[44:45], 1, v[26:27]
	s_mov_b32 s13, 0
	s_waitcnt vmcnt(0)
	s_branch .LBB0_254
